# attention phase: static s_setprio 1 for waves 4-7 (reset at phase exit)
# speedup vs baseline: 1.0049x; 1.0049x over previous
; #define LAS __attribute__((address_space(3)))
; DI int tid_opaque() { int t = threadIdx.x; asm volatile("" : "+v"(t)); return t; }
; DI void attn_phase(unsigned char* ws, LAS unsigned char* lds, unsigned* ctr, bool never) {
;     const int tid = tid_opaque();
;     for (;;) {
;         __syncthreads();
;         if (tid == 0) *(LAS int*)(lds + AT_MISC) = (int)atomicAdd(ctr, 1u);
;         __syncthreads();
;         const int u = *(LAS int*)(lds + AT_MISC);
;         if (u >= 3072) break;
;         if (u < 2048) { const int qb = 15 - (u >> 7), rem = u & 127, ty = rem >> 6, bh = rem & 63;
;     ...
;             if (ty == 0) { attn_unit<0>(ws, bh >> 3, bh & 7, qb, lds, never); __syncthreads(); } else { attn_unit<2>(ws, bh >> 3, bh & 7, qb, lds, never); __syncthreads(); }
;     ...
;             if (ty == 0) attn_unit<0>(ws, bh >> 3, bh & 7, qb, lds); else attn_unit<2>(ws, bh >> 3, bh & 7, qb, lds); }
;         else { const int v = u - 2048, qb = 15 - (v >> 6), bh = v & 63;
;     ...
;             attn_unit<1>(ws, bh >> 3, bh & 7, qb, lds, never); __syncthreads();
;     ...
;             attn_unit<1>(ws, bh >> 3, bh & 7, qb, lds); }
;     }
; }
; __global__ void __launch_bounds__(NTHREADS, 2) fwd_kernel(Params p_unused) {
;     ...
;         } else if (s == 3) {
;             unsigned char* ws = pp->ws;
;             attn_phase(ws, lds, (unsigned*)(ws + WS_CTR) + l, ph_hi == 12345);
.LBB0_92:
	s_cmp_eq_u32 s41, 3
	s_mov_b64 s[16:17], -1
	s_cbranch_scc0 .LBB0_225
	s_load_dwordx2 s[14:15], s[0:1], 0xa0
	v_readfirstlane_b32 s2, v210
	s_cmpk_lt_u32 s2, 0x100
	s_cbranch_scc1 .Latt_noprio
	s_setprio 1
.Latt_noprio:
	s_ashr_i32 s73, s72, 31
	s_lshl_b64 s[16:17], s[72:73], 2
	v_mov_b32_e32 v0, v210
	s_waitcnt lgkmcnt(0)
	s_add_u32 s16, s14, s16
	s_addc_u32 s17, s15, s17
	s_add_u32 s18, s14, 0xba00000
	s_addc_u32 s19, s15, 0
	s_add_u32 s20, s14, 0x11a00000
	s_addc_u32 s21, s15, 0
	s_add_u32 s22, s14, 0x17a00000
	s_addc_u32 s23, s15, 0
	s_add_u32 s24, s14, 0x1aa00000
	s_addc_u32 s25, s15, 0
	s_add_u32 s26, s14, 0xb800000
	s_addc_u32 s27, s15, 0
	s_add_u32 s28, s14, 0x7800000
	s_addc_u32 s29, s15, 0
	s_add_u32 s9, s14, 0x300000
	v_cmp_eq_u32_e64 s[42:43], 0, v0
	s_addc_u32 s13, s15, 0
	s_branch .LBB0_97

; DI void attn_phase(unsigned char* ws, LAS unsigned char* lds, unsigned* ctr, bool never) {
;     ...
;         if (u >= 3072) break;
; __global__ void __launch_bounds__(NTHREADS, 2) fwd_kernel(Params p_unused) {
;     ...
;             attn_phase(ws, lds, (unsigned*)(ws + WS_CTR) + l, ph_hi == 12345);
.LBB0_224:
	s_setprio 0
	s_mov_b64 s[16:17], 0
